# P4 exclusive shift of the h totals uses DPP zero-fill (bound_ctrl) instead of eight v_mov zero inits (on top of the DPP-fused local scan)
# speedup vs baseline: 1.0025x; 1.0020x over previous
.LBB0_464:
	s_lshl_b32 s6, s62, 7
	v_mov_b32_e32 v239, v224
	v_mov_b32_e32 v237, v225
	s_or_b32 s6, s6, s96
	s_nop 0
	v_lshl_add_u32 v238, v237, 3, s6
	s_lshl_b32 s6, s63, 8
	s_add_i32 s6, s6, s16
	v_lshl_add_u32 v171, v239, 3, s6
	v_lshlrev_b32_e32 v232, 1, v238
	v_lshlrev_b32_e32 v233, 11, v171
	v_lshlrev_b32_e32 v92, 2, v238
	v_add_u32_e32 v164, v233, v232
	v_or_b32_e32 v235, 0x1000, v233
	global_load_dwordx4 v[184:187], v92, s[2:3] offset:16
	global_load_dwordx4 v[188:191], v92, s[2:3]
	global_load_dwordx4 v[192:195], v92, s[12:13] offset:16
	global_load_dwordx4 v[196:199], v92, s[12:13]
	global_load_dwordx4 v[240:243], v92, s[36:37] offset:16
	global_load_dwordx4 v[200:203], v92, s[36:37]
	v_or_b32_e32 v234, 0x800, v233
	v_add_u32_e32 v180, v235, v232
	v_or_b32_e32 v236, 0x1800, v233
	v_add_u32_e32 v176, 0x2000, v164
	v_add_u32_e32 v172, 0x3000, v164
	v_add_u32_e32 v182, v234, v232
	global_load_dwordx4 v[244:247], v164, s[26:27]
	global_load_dwordx4 v[152:155], v182, s[26:27]
	v_add_u32_e32 v178, v236, v232
	global_load_dwordx4 v[148:151], v180, s[26:27]
	global_load_dwordx4 v[144:147], v178, s[26:27]
	v_add_u32_e32 v174, 0x2800, v164
	global_load_dwordx4 v[140:143], v176, s[26:27]
	global_load_dwordx4 v[132:135], v174, s[26:27]
	v_add_u32_e32 v170, 0x3800, v164
	global_load_dwordx4 v[112:115], v172, s[26:27]
	global_load_dwordx4 v[92:95], v170, s[26:27]
	v_and_b32_e32 v171, 0x1ff8, v171
	s_waitcnt vmcnt(0)
	v_pk_mul_f32 v[204:205], v[186:187], s[48:49] op_sel_hi:[1,0]
	v_pk_mul_f32 v[216:217], v[190:191], s[48:49] op_sel_hi:[1,0]
	v_pk_mul_f32 v[222:223], v[188:189], s[48:49] op_sel_hi:[1,0]
	v_pk_mul_f32 v[214:215], v[198:199], s[48:49] op_sel_hi:[1,0]
	v_pk_mul_f32 v[220:221], v[196:197], s[48:49] op_sel_hi:[1,0]
	v_pk_mul_f32 v[212:213], v[202:203], s[50:51] op_sel_hi:[1,0]
	v_pk_mul_f32 v[218:219], v[200:201], s[50:51] op_sel_hi:[1,0]
	v_pk_mul_f32 v[202:203], v[194:195], s[48:49] op_sel_hi:[1,0]
	v_pk_mul_f32 v[200:201], v[242:243], s[50:51] op_sel_hi:[1,0]
	v_pk_mul_f32 v[210:211], v[184:185], s[48:49] op_sel_hi:[1,0]
	v_pk_mul_f32 v[208:209], v[192:193], s[48:49] op_sel_hi:[1,0]
	v_pk_mul_f32 v[206:207], v[240:241], s[50:51] op_sel_hi:[1,0]
	v_fmamk_f32 v136, v136, 0xbfb8aa3b, v222
	v_exp_f32_e32 v136, v136
	v_fmamk_f32 v128, v128, 0xbfb8aa3b, v220
	v_fmamk_f32 v137, v137, 0xbfb8aa3b, v223
	v_exp_f32_e32 v128, v128
	v_add_f32_e32 v136, 1.0, v136
	v_rcp_f32_e32 v136, v136
	v_exp_f32_e32 v137, v137
	v_add_f32_e32 v128, 1.0, v128
	v_rcp_f32_e32 v128, v128
	v_mul_f32_e32 v136, v218, v136
	v_exp_f32_e32 v136, v136
	v_add_f32_e32 v137, 1.0, v137
	v_rcp_f32_e32 v175, v137
	v_cmp_eq_u32_e32 vcc, 0, v171
	v_fma_f32 v173, -v136, v136, 1.0
	v_sqrt_f32_e32 v173, v173
	v_fmamk_f32 v129, v129, 0xbfb8aa3b, v221
	v_exp_f32_e32 v129, v129
	v_lshlrev_b32_e32 v185, 16, v244
	v_cndmask_b32_e64 v137, v173, 1.0, vcc
	v_mul_f32_e32 v137, v128, v137
	v_mul_f32_e32 v128, v219, v175
	v_exp_f32_e32 v128, v128
	v_and_b32_e32 v187, 0xffff0000, v244
	v_mov_b32_e32 v184, v165
	v_mul_f32_e32 v186, v137, v185
	v_fma_f32 v171, -v128, v128, 1.0
	v_sqrt_f32_e32 v171, v171
	v_add_f32_e32 v129, 1.0, v129
	v_fmamk_f32 v138, v138, 0xbfb8aa3b, v216
	v_pk_fma_f32 v[184:185], v[136:137], v[184:185], v[186:187] op_sel_hi:[1,1,0]
	v_rcp_f32_e32 v129, v129
	v_cndmask_b32_e64 v137, v171, 1.0, vcc
	v_exp_f32_e32 v171, v138
	v_fmamk_f32 v130, v130, 0xbfb8aa3b, v214
	v_mul_f32_e32 v129, v129, v137
	v_exp_f32_e32 v130, v130
	v_add_f32_e32 v137, 1.0, v171
	v_rcp_f32_e32 v137, v137
	v_mov_b32_e32 v186, v165
	v_mul_f32_e32 v138, v129, v187
	v_pk_fma_f32 v[186:187], v[128:129], v[186:187], v[138:139] op_sel_hi:[1,1,0]
	v_mul_f32_e32 v129, v212, v137
	v_exp_f32_e32 v138, v129
	v_add_f32_e32 v129, 1.0, v130
	v_fmamk_f32 v130, v139, 0xbfb8aa3b, v217
	v_exp_f32_e32 v130, v130
	v_fma_f32 v137, -v138, v138, 1.0
	v_sqrt_f32_e32 v137, v137
	v_rcp_f32_e32 v129, v129
	v_add_f32_e32 v130, 1.0, v130
	v_rcp_f32_e32 v130, v130
	v_cndmask_b32_e64 v137, v137, 1.0, vcc
	v_mul_f32_e32 v139, v129, v137
	v_fmamk_f32 v124, v124, 0xbfb8aa3b, v210
	v_mul_f32_e32 v129, v213, v130
	v_exp_f32_e32 v130, v129
	v_fmamk_f32 v129, v131, 0xbfb8aa3b, v215
	v_exp_f32_e32 v129, v129
	v_exp_f32_e32 v137, v124
	v_fma_f32 v131, -v130, v130, 1.0
	v_sqrt_f32_e32 v131, v131
	v_add_f32_e32 v129, 1.0, v129
	v_rcp_f32_e32 v129, v129
	v_lshlrev_b32_e32 v189, 16, v245
	v_cndmask_b32_e64 v131, v131, 1.0, vcc
	v_and_b32_e32 v191, 0xffff0000, v245
	v_mul_f32_e32 v131, v129, v131
	v_add_f32_e32 v129, 1.0, v137
	v_rcp_f32_e32 v129, v129
	v_mov_b32_e32 v188, v165
	v_mul_f32_e32 v190, v139, v189
	v_pk_fma_f32 v[188:189], v[138:139], v[188:189], v[190:191] op_sel_hi:[1,1,0]
	v_mov_b32_e32 v190, v165
	v_mul_f32_e32 v124, v131, v191
	v_pk_fma_f32 v[190:191], v[130:131], v[190:191], v[124:125] op_sel_hi:[1,1,0]
	v_mul_f32_e32 v124, v206, v129
	v_fmamk_f32 v120, v120, 0xbfb8aa3b, v208
	v_exp_f32_e32 v124, v124
	v_fmamk_f32 v125, v125, 0xbfb8aa3b, v211
	v_exp_f32_e32 v120, v120
	v_exp_f32_e32 v125, v125
	v_fma_f32 v129, -v124, v124, 1.0
	v_sqrt_f32_e32 v129, v129
	v_add_f32_e32 v120, 1.0, v120
	v_add_f32_e32 v125, 1.0, v125
	v_rcp_f32_e32 v120, v120
	v_rcp_f32_e32 v131, v125
	v_cndmask_b32_e64 v125, v129, 1.0, vcc
	v_fmamk_f32 v121, v121, 0xbfb8aa3b, v209
	v_mul_f32_e32 v125, v120, v125
	v_mul_f32_e32 v120, v207, v131
	v_exp_f32_e32 v120, v120
	v_exp_f32_e32 v121, v121
	v_lshlrev_b32_e32 v193, 16, v246
	v_and_b32_e32 v195, 0xffff0000, v246
	v_fma_f32 v129, -v120, v120, 1.0
	v_sqrt_f32_e32 v129, v129
	v_mov_b32_e32 v192, v165
	v_mul_f32_e32 v194, v125, v193
	v_add_f32_e32 v121, 1.0, v121
	v_fmamk_f32 v126, v126, 0xbfb8aa3b, v204
	v_pk_fma_f32 v[192:193], v[124:125], v[192:193], v[194:195] op_sel_hi:[1,1,0]
	v_rcp_f32_e32 v121, v121
	v_cndmask_b32_e64 v125, v129, 1.0, vcc
	v_exp_f32_e32 v129, v126
	v_mov_b32_e32 v194, v165
	v_mul_f32_e32 v121, v121, v125
	v_mul_f32_e32 v126, v121, v195
	v_add_f32_e32 v125, 1.0, v129
	v_rcp_f32_e32 v125, v125
	v_pk_fma_f32 v[194:195], v[120:121], v[194:195], v[126:127] op_sel_hi:[1,1,0]
	v_fmamk_f32 v122, v122, 0xbfb8aa3b, v202
	v_exp_f32_e32 v129, v122
	v_mul_f32_e32 v121, v200, v125
	v_fmamk_f32 v125, v127, 0xbfb8aa3b, v205
	v_exp_f32_e32 v125, v125
	v_exp_f32_e32 v122, v121
	v_fmamk_f32 v123, v123, 0xbfb8aa3b, v203
	v_add_f32_e32 v121, 1.0, v129
	v_add_f32_e32 v125, 1.0, v125
	v_fma_f32 v126, -v122, v122, 1.0
	v_rcp_f32_e32 v125, v125
	v_sqrt_f32_e32 v126, v126
	v_exp_f32_e32 v129, v123
	v_rcp_f32_e32 v121, v121
	v_mul_f32_e32 v123, v201, v125
	v_cndmask_b32_e64 v127, v126, 1.0, vcc
	v_exp_f32_e32 v126, v123
	v_mul_f32_e32 v123, v121, v127
	v_add_f32_e32 v121, 1.0, v129
	v_rcp_f32_e32 v121, v121
	v_fma_f32 v125, -v126, v126, 1.0
	v_sqrt_f32_e32 v125, v125
	v_lshlrev_b32_e32 v197, 16, v247
	v_and_b32_e32 v199, 0xffff0000, v247
	v_mov_b32_e32 v196, v165
	v_mul_f32_e32 v198, v123, v197
	v_pk_fma_f32 v[196:197], v[122:123], v[196:197], v[198:199] op_sel_hi:[1,1,0]
	v_cndmask_b32_e64 v123, v125, 1.0, vcc
	v_mul_f32_e32 v127, v121, v123
	v_mov_b32_e32 v198, v165
	v_mul_f32_e32 v240, v127, v199
	v_pk_fma_f32 v[198:199], v[126:127], v[198:199], v[240:241] op_sel_hi:[1,1,0]
	v_fmamk_f32 v116, v116, 0xbfb8aa3b, v222
	v_exp_f32_e32 v116, v116
	v_fmamk_f32 v108, v108, 0xbfb8aa3b, v220
	v_exp_f32_e32 v108, v108
	v_fmamk_f32 v117, v117, 0xbfb8aa3b, v223
	v_add_f32_e32 v116, 1.0, v116
	v_rcp_f32_e32 v116, v116
	v_add_f32_e32 v108, 1.0, v108
	v_rcp_f32_e32 v108, v108
	v_exp_f32_e32 v121, v117
	v_mul_f32_e32 v116, v218, v116
	v_exp_f32_e32 v241, v116
	v_fmamk_f32 v109, v109, 0xbfb8aa3b, v221
	v_exp_f32_e32 v123, v109
	v_lshlrev_b32_e32 v242, 16, v153
	v_fma_f32 v116, -v241, v241, 1.0
	v_sqrt_f32_e32 v116, v116
	v_and_b32_e32 v244, 0xffff0000, v153
	v_lshlrev_b32_e32 v240, 16, v152
	v_mov_b32_e32 v117, v184
	v_mul_f32_e32 v116, v108, v116
	v_add_f32_e32 v108, 1.0, v121
	v_rcp_f32_e32 v121, v108
	v_mul_f32_e32 v108, v184, v241
	v_fmamk_f32 v110, v110, 0xbfb8aa3b, v214
	v_exp_f32_e32 v110, v110
	v_mul_f32_e32 v109, v219, v121
	v_exp_f32_e32 v153, v109
	v_pk_fma_f32 v[108:109], v[116:117], v[240:241], v[108:109] op_sel_hi:[1,1,0]
	v_and_b32_e32 v152, 0xffff0000, v152
	v_add_f32_e32 v109, 1.0, v123
	v_rcp_f32_e32 v116, v109
	v_fma_f32 v109, -v153, v153, 1.0
	v_sqrt_f32_e32 v117, v109
	v_fmamk_f32 v109, v118, 0xbfb8aa3b, v216
	v_exp_f32_e32 v118, v109
	v_add_f32_e32 v110, 1.0, v110
	v_mul_f32_e32 v116, v116, v117
	v_mov_b32_e32 v117, v186
	v_add_f32_e32 v118, 1.0, v118
	v_rcp_f32_e32 v121, v118
	v_mul_f32_e32 v118, v186, v153
	v_pk_fma_f32 v[116:117], v[116:117], v[152:153], v[118:119] op_sel_hi:[1,1,0]
	v_rcp_f32_e32 v110, v110
	v_mul_f32_e32 v121, v212, v121
	v_exp_f32_e32 v243, v121
	v_fmamk_f32 v104, v104, 0xbfb8aa3b, v210
	v_exp_f32_e32 v104, v104
	v_fmamk_f32 v111, v111, 0xbfb8aa3b, v215
	v_fma_f32 v117, -v243, v243, 1.0
	v_sqrt_f32_e32 v118, v117
	v_fmamk_f32 v117, v119, 0xbfb8aa3b, v217
	v_exp_f32_e32 v121, v117
	v_exp_f32_e32 v123, v111
	v_mul_f32_e32 v118, v110, v118
	v_add_f32_e32 v104, 1.0, v104
	v_add_f32_e32 v110, 1.0, v121
	v_rcp_f32_e32 v121, v110
	v_mov_b32_e32 v119, v188
	v_mul_f32_e32 v110, v188, v243
	v_fmamk_f32 v100, v100, 0xbfb8aa3b, v208
	v_mul_f32_e32 v111, v213, v121
	v_exp_f32_e32 v245, v111
	v_rcp_f32_e32 v121, v104
	v_pk_fma_f32 v[110:111], v[118:119], v[242:243], v[110:111] op_sel_hi:[1,1,0]
	v_exp_f32_e32 v100, v100
	v_add_f32_e32 v111, 1.0, v123
	v_rcp_f32_e32 v118, v111
	v_fma_f32 v111, -v245, v245, 1.0
	v_sqrt_f32_e32 v119, v111
	v_mul_f32_e32 v121, v206, v121
	v_exp_f32_e32 v247, v121
	v_mul_f32_e32 v104, v190, v245
	v_mul_f32_e32 v118, v118, v119
	v_mov_b32_e32 v119, v190
	v_pk_fma_f32 v[118:119], v[118:119], v[244:245], v[104:105] op_sel_hi:[1,1,0]
	v_add_f32_e32 v100, 1.0, v100
	v_fma_f32 v104, -v247, v247, 1.0
	v_fmamk_f32 v105, v105, 0xbfb8aa3b, v211
	v_rcp_f32_e32 v100, v100
	v_sqrt_f32_e32 v104, v104
	v_exp_f32_e32 v121, v105
	v_fmamk_f32 v101, v101, 0xbfb8aa3b, v209
	v_exp_f32_e32 v123, v101
	v_mul_f32_e32 v104, v100, v104
	v_add_f32_e32 v100, 1.0, v121
	v_rcp_f32_e32 v121, v100
	v_lshlrev_b32_e32 v248, 16, v155
	v_and_b32_e32 v250, 0xffff0000, v155
	v_lshlrev_b32_e32 v246, 16, v154
	v_mul_f32_e32 v101, v207, v121
	v_exp_f32_e32 v155, v101
	v_mov_b32_e32 v105, v192
	v_mul_f32_e32 v100, v192, v247
	v_pk_fma_f32 v[100:101], v[104:105], v[246:247], v[100:101] op_sel_hi:[1,1,0]
	v_fmamk_f32 v102, v102, 0xbfb8aa3b, v202
	v_add_f32_e32 v101, 1.0, v123
	v_rcp_f32_e32 v104, v101
	v_fma_f32 v101, -v155, v155, 1.0
	v_sqrt_f32_e32 v105, v101
	v_fmamk_f32 v101, v106, 0xbfb8aa3b, v204
	v_exp_f32_e32 v106, v101
	v_and_b32_e32 v154, 0xffff0000, v154
	v_mul_f32_e32 v104, v104, v105
	v_mov_b32_e32 v105, v194
	v_add_f32_e32 v106, 1.0, v106
	v_rcp_f32_e32 v106, v106
	v_exp_f32_e32 v121, v102
	v_mul_f32_e32 v102, v194, v155
	v_pk_fma_f32 v[104:105], v[104:105], v[154:155], v[102:103] op_sel_hi:[1,1,0]
	v_fmamk_f32 v103, v103, 0xbfb8aa3b, v203
	v_mul_f32_e32 v105, v200, v106
	v_exp_f32_e32 v249, v105
	v_fmamk_f32 v105, v107, 0xbfb8aa3b, v205
	v_exp_f32_e32 v106, v105
	v_add_f32_e32 v102, 1.0, v121
	v_fma_f32 v105, -v249, v249, 1.0
	v_rcp_f32_e32 v102, v102
	v_add_f32_e32 v106, 1.0, v106
	v_sqrt_f32_e32 v107, v105
	v_rcp_f32_e32 v106, v106
	v_mul_f32_e32 v109, v136, v241
	v_mul_f32_e32 v117, v128, v153
	v_mul_f32_e32 v102, v102, v107
	v_exp_f32_e32 v107, v103
	v_mul_f32_e32 v103, v201, v106
	v_exp_f32_e32 v251, v103
	v_mov_b32_e32 v103, v196
	v_add_f32_e32 v106, 1.0, v107
	v_rcp_f32_e32 v107, v106
	v_fma_f32 v106, -v251, v251, 1.0
	v_sqrt_f32_e32 v121, v106
	v_mul_f32_e32 v106, v196, v249
	v_pk_fma_f32 v[102:103], v[102:103], v[248:249], v[106:107] op_sel_hi:[1,1,0]
	v_mul_f32_e32 v152, v198, v251
	v_mul_f32_e32 v106, v107, v121
	v_mov_b32_e32 v107, v198
	v_pk_fma_f32 v[106:107], v[106:107], v[250:251], v[152:153] op_sel_hi:[1,1,0]
	v_mul_f32_e32 v111, v138, v243
	v_mul_f32_e32 v119, v130, v245
	v_mul_f32_e32 v101, v124, v247
	v_mul_f32_e32 v105, v120, v155
	v_mul_f32_e32 v103, v122, v249
	v_mul_f32_e32 v107, v126, v251
	v_fmamk_f32 v96, v96, 0xbfb8aa3b, v222
	v_exp_f32_e32 v96, v96
	v_fmamk_f32 v88, v88, 0xbfb8aa3b, v220
	v_exp_f32_e32 v88, v88
	v_fmamk_f32 v97, v97, 0xbfb8aa3b, v223
	v_add_f32_e32 v96, 1.0, v96
	v_rcp_f32_e32 v96, v96
	v_add_f32_e32 v88, 1.0, v88
	v_rcp_f32_e32 v88, v88
	v_exp_f32_e32 v121, v97
	v_mul_f32_e32 v96, v218, v96
	v_exp_f32_e32 v153, v96
	v_fmamk_f32 v89, v89, 0xbfb8aa3b, v221
	v_exp_f32_e32 v123, v89
	v_lshlrev_b32_e32 v154, 16, v149
	v_fma_f32 v96, -v153, v153, 1.0
	v_sqrt_f32_e32 v96, v96
	v_and_b32_e32 v240, 0xffff0000, v149
	v_lshlrev_b32_e32 v152, 16, v148
	v_mov_b32_e32 v97, v108
	v_mul_f32_e32 v96, v88, v96
	v_add_f32_e32 v88, 1.0, v121
	v_rcp_f32_e32 v121, v88
	v_mul_f32_e32 v88, v108, v153
	v_fmamk_f32 v90, v90, 0xbfb8aa3b, v214
	v_exp_f32_e32 v90, v90
	v_mul_f32_e32 v89, v219, v121
	v_exp_f32_e32 v149, v89
	v_pk_fma_f32 v[88:89], v[96:97], v[152:153], v[88:89] op_sel_hi:[1,1,0]
	v_and_b32_e32 v148, 0xffff0000, v148
	v_add_f32_e32 v89, 1.0, v123
	v_rcp_f32_e32 v96, v89
	v_fma_f32 v89, -v149, v149, 1.0
	v_sqrt_f32_e32 v97, v89
	v_fmamk_f32 v89, v98, 0xbfb8aa3b, v216
	v_exp_f32_e32 v98, v89
	v_add_f32_e32 v90, 1.0, v90
	v_mul_f32_e32 v96, v96, v97
	v_mov_b32_e32 v97, v116
	v_add_f32_e32 v98, 1.0, v98
	v_rcp_f32_e32 v121, v98
	v_mul_f32_e32 v98, v116, v149
	v_pk_fma_f32 v[96:97], v[96:97], v[148:149], v[98:99] op_sel_hi:[1,1,0]
	v_rcp_f32_e32 v90, v90
	v_mul_f32_e32 v121, v212, v121
	v_exp_f32_e32 v155, v121
	v_fmamk_f32 v84, v84, 0xbfb8aa3b, v210
	v_exp_f32_e32 v84, v84
	v_fmamk_f32 v91, v91, 0xbfb8aa3b, v215
	v_fma_f32 v97, -v155, v155, 1.0
	v_sqrt_f32_e32 v98, v97
	v_fmamk_f32 v97, v99, 0xbfb8aa3b, v217
	v_exp_f32_e32 v121, v97
	v_exp_f32_e32 v123, v91
	v_mul_f32_e32 v98, v90, v98
	v_add_f32_e32 v84, 1.0, v84
	v_add_f32_e32 v90, 1.0, v121
	v_rcp_f32_e32 v121, v90
	v_mov_b32_e32 v99, v110
	v_mul_f32_e32 v90, v110, v155
	v_fmamk_f32 v80, v80, 0xbfb8aa3b, v208
	v_mul_f32_e32 v91, v213, v121
	v_exp_f32_e32 v241, v91
	v_rcp_f32_e32 v121, v84
	v_pk_fma_f32 v[90:91], v[98:99], v[154:155], v[90:91] op_sel_hi:[1,1,0]
	v_exp_f32_e32 v80, v80
	v_add_f32_e32 v91, 1.0, v123
	v_rcp_f32_e32 v98, v91
	v_fma_f32 v91, -v241, v241, 1.0
	v_sqrt_f32_e32 v99, v91
	v_mul_f32_e32 v121, v206, v121
	v_exp_f32_e32 v243, v121
	v_mul_f32_e32 v84, v118, v241
	v_mul_f32_e32 v98, v98, v99
	v_mov_b32_e32 v99, v118
	v_pk_fma_f32 v[98:99], v[98:99], v[240:241], v[84:85] op_sel_hi:[1,1,0]
	v_add_f32_e32 v80, 1.0, v80
	v_fma_f32 v84, -v243, v243, 1.0
	v_fmamk_f32 v85, v85, 0xbfb8aa3b, v211
	v_rcp_f32_e32 v80, v80
	v_sqrt_f32_e32 v84, v84
	v_exp_f32_e32 v121, v85
	v_fmamk_f32 v81, v81, 0xbfb8aa3b, v209
	v_exp_f32_e32 v123, v81
	v_mul_f32_e32 v84, v80, v84
	v_add_f32_e32 v80, 1.0, v121
	v_rcp_f32_e32 v121, v80
	v_lshlrev_b32_e32 v244, 16, v151
	v_and_b32_e32 v246, 0xffff0000, v151
	v_lshlrev_b32_e32 v242, 16, v150
	v_mul_f32_e32 v81, v207, v121
	v_exp_f32_e32 v151, v81
	v_mov_b32_e32 v85, v100
	v_mul_f32_e32 v80, v100, v243
	v_pk_fma_f32 v[80:81], v[84:85], v[242:243], v[80:81] op_sel_hi:[1,1,0]
	v_fmamk_f32 v82, v82, 0xbfb8aa3b, v202
	v_add_f32_e32 v81, 1.0, v123
	v_rcp_f32_e32 v84, v81
	v_fma_f32 v81, -v151, v151, 1.0
	v_sqrt_f32_e32 v85, v81
	v_fmamk_f32 v81, v86, 0xbfb8aa3b, v204
	v_exp_f32_e32 v86, v81
	v_and_b32_e32 v150, 0xffff0000, v150
	v_mul_f32_e32 v84, v84, v85
	v_mov_b32_e32 v85, v104
	v_add_f32_e32 v86, 1.0, v86
	v_rcp_f32_e32 v86, v86
	v_exp_f32_e32 v121, v82
	v_mul_f32_e32 v82, v104, v151
	v_pk_fma_f32 v[84:85], v[84:85], v[150:151], v[82:83] op_sel_hi:[1,1,0]
	v_fmamk_f32 v83, v83, 0xbfb8aa3b, v203
	v_mul_f32_e32 v85, v200, v86
	v_exp_f32_e32 v245, v85
	v_fmamk_f32 v85, v87, 0xbfb8aa3b, v205
	v_exp_f32_e32 v86, v85
	v_add_f32_e32 v82, 1.0, v121
	v_fma_f32 v85, -v245, v245, 1.0
	v_rcp_f32_e32 v82, v82
	v_add_f32_e32 v86, 1.0, v86
	v_sqrt_f32_e32 v87, v85
	v_rcp_f32_e32 v86, v86
	v_mul_f32_e32 v89, v153, v109
	v_mul_f32_e32 v97, v149, v117
	v_mul_f32_e32 v82, v82, v87
	v_exp_f32_e32 v87, v83
	v_mul_f32_e32 v83, v201, v86
	v_exp_f32_e32 v247, v83
	v_mov_b32_e32 v83, v102
	v_add_f32_e32 v86, 1.0, v87
	v_rcp_f32_e32 v87, v86
	v_fma_f32 v86, -v247, v247, 1.0
	v_sqrt_f32_e32 v121, v86
	v_mul_f32_e32 v86, v102, v245
	v_pk_fma_f32 v[82:83], v[82:83], v[244:245], v[86:87] op_sel_hi:[1,1,0]
	v_mul_f32_e32 v148, v106, v247
	v_mul_f32_e32 v86, v87, v121
	v_mov_b32_e32 v87, v106
	v_pk_fma_f32 v[86:87], v[86:87], v[246:247], v[148:149] op_sel_hi:[1,1,0]
	v_mul_f32_e32 v91, v155, v111
	v_mul_f32_e32 v99, v241, v119
	v_mul_f32_e32 v81, v243, v101
	v_mul_f32_e32 v85, v151, v105
	v_mul_f32_e32 v83, v245, v103
	v_mul_f32_e32 v87, v247, v107
	v_fmamk_f32 v76, v76, 0xbfb8aa3b, v222
	v_exp_f32_e32 v76, v76
	v_fmamk_f32 v72, v72, 0xbfb8aa3b, v220
	v_exp_f32_e32 v72, v72
	v_fmamk_f32 v77, v77, 0xbfb8aa3b, v223
	v_add_f32_e32 v76, 1.0, v76
	v_rcp_f32_e32 v76, v76
	v_add_f32_e32 v72, 1.0, v72
	v_rcp_f32_e32 v72, v72
	v_exp_f32_e32 v121, v77
	v_mul_f32_e32 v76, v218, v76
	v_exp_f32_e32 v149, v76
	v_fmamk_f32 v73, v73, 0xbfb8aa3b, v221
	v_exp_f32_e32 v123, v73
	v_lshlrev_b32_e32 v150, 16, v145
	v_fma_f32 v76, -v149, v149, 1.0
	v_sqrt_f32_e32 v76, v76
	v_and_b32_e32 v152, 0xffff0000, v145
	v_lshlrev_b32_e32 v148, 16, v144
	v_mov_b32_e32 v77, v88
	v_mul_f32_e32 v76, v72, v76
	v_add_f32_e32 v72, 1.0, v121
	v_rcp_f32_e32 v121, v72
	v_mul_f32_e32 v72, v88, v149
	v_fmamk_f32 v74, v74, 0xbfb8aa3b, v214
	v_exp_f32_e32 v74, v74
	v_mul_f32_e32 v73, v219, v121
	v_exp_f32_e32 v145, v73
	v_pk_fma_f32 v[72:73], v[76:77], v[148:149], v[72:73] op_sel_hi:[1,1,0]
	v_and_b32_e32 v144, 0xffff0000, v144
	v_add_f32_e32 v73, 1.0, v123
	v_rcp_f32_e32 v76, v73
	v_fma_f32 v73, -v145, v145, 1.0
	v_sqrt_f32_e32 v77, v73
	v_fmamk_f32 v73, v78, 0xbfb8aa3b, v216
	v_exp_f32_e32 v78, v73
	v_add_f32_e32 v74, 1.0, v74
	v_mul_f32_e32 v76, v76, v77
	v_mov_b32_e32 v77, v96
	v_add_f32_e32 v78, 1.0, v78
	v_rcp_f32_e32 v121, v78
	v_mul_f32_e32 v78, v96, v145
	v_pk_fma_f32 v[76:77], v[76:77], v[144:145], v[78:79] op_sel_hi:[1,1,0]
	v_rcp_f32_e32 v74, v74
	v_mul_f32_e32 v121, v212, v121
	v_exp_f32_e32 v151, v121
	v_fmamk_f32 v68, v68, 0xbfb8aa3b, v210
	v_exp_f32_e32 v68, v68
	v_fmamk_f32 v75, v75, 0xbfb8aa3b, v215
	v_fma_f32 v77, -v151, v151, 1.0
	v_sqrt_f32_e32 v78, v77
	v_fmamk_f32 v77, v79, 0xbfb8aa3b, v217
	v_exp_f32_e32 v121, v77
	v_exp_f32_e32 v123, v75
	v_mul_f32_e32 v78, v74, v78
	v_add_f32_e32 v68, 1.0, v68
	v_add_f32_e32 v74, 1.0, v121
	v_rcp_f32_e32 v121, v74
	v_mov_b32_e32 v79, v90
	v_mul_f32_e32 v74, v90, v151
	v_fmamk_f32 v64, v64, 0xbfb8aa3b, v208
	v_mul_f32_e32 v75, v213, v121
	v_exp_f32_e32 v153, v75
	v_rcp_f32_e32 v121, v68
	v_pk_fma_f32 v[74:75], v[78:79], v[150:151], v[74:75] op_sel_hi:[1,1,0]
	v_exp_f32_e32 v64, v64
	v_add_f32_e32 v75, 1.0, v123
	v_rcp_f32_e32 v78, v75
	v_fma_f32 v75, -v153, v153, 1.0
	v_sqrt_f32_e32 v79, v75
	v_mul_f32_e32 v121, v206, v121
	v_exp_f32_e32 v155, v121
	v_mul_f32_e32 v68, v98, v153
	v_mul_f32_e32 v78, v78, v79
	v_mov_b32_e32 v79, v98
	v_pk_fma_f32 v[78:79], v[78:79], v[152:153], v[68:69] op_sel_hi:[1,1,0]
	v_add_f32_e32 v64, 1.0, v64
	v_fma_f32 v68, -v155, v155, 1.0
	v_fmamk_f32 v69, v69, 0xbfb8aa3b, v211
	v_rcp_f32_e32 v64, v64
	v_sqrt_f32_e32 v68, v68
	v_exp_f32_e32 v121, v69
	v_fmamk_f32 v65, v65, 0xbfb8aa3b, v209
	v_exp_f32_e32 v123, v65
	v_mul_f32_e32 v68, v64, v68
	v_add_f32_e32 v64, 1.0, v121
	v_rcp_f32_e32 v121, v64
	v_lshlrev_b32_e32 v240, 16, v147
	v_and_b32_e32 v242, 0xffff0000, v147
	v_lshlrev_b32_e32 v154, 16, v146
	v_mul_f32_e32 v65, v207, v121
	v_exp_f32_e32 v147, v65
	v_mov_b32_e32 v69, v80
	v_mul_f32_e32 v64, v80, v155
	v_pk_fma_f32 v[64:65], v[68:69], v[154:155], v[64:65] op_sel_hi:[1,1,0]
	v_fmamk_f32 v66, v66, 0xbfb8aa3b, v202
	v_add_f32_e32 v65, 1.0, v123
	v_rcp_f32_e32 v68, v65
	v_fma_f32 v65, -v147, v147, 1.0
	v_sqrt_f32_e32 v69, v65
	v_fmamk_f32 v65, v70, 0xbfb8aa3b, v204
	v_exp_f32_e32 v70, v65
	v_and_b32_e32 v146, 0xffff0000, v146
	v_mul_f32_e32 v68, v68, v69
	v_mov_b32_e32 v69, v84
	v_add_f32_e32 v70, 1.0, v70
	v_rcp_f32_e32 v70, v70
	v_exp_f32_e32 v121, v66
	v_mul_f32_e32 v66, v84, v147
	v_pk_fma_f32 v[68:69], v[68:69], v[146:147], v[66:67] op_sel_hi:[1,1,0]
	v_fmamk_f32 v67, v67, 0xbfb8aa3b, v203
	v_mul_f32_e32 v69, v200, v70
	v_exp_f32_e32 v241, v69
	v_fmamk_f32 v69, v71, 0xbfb8aa3b, v205
	v_exp_f32_e32 v70, v69
	v_add_f32_e32 v66, 1.0, v121
	v_fma_f32 v69, -v241, v241, 1.0
	v_rcp_f32_e32 v66, v66
	v_add_f32_e32 v70, 1.0, v70
	v_sqrt_f32_e32 v71, v69
	v_rcp_f32_e32 v70, v70
	v_mul_f32_e32 v73, v149, v89
	v_mul_f32_e32 v77, v145, v97
	v_mul_f32_e32 v66, v66, v71
	v_exp_f32_e32 v71, v67
	v_mul_f32_e32 v67, v201, v70
	v_exp_f32_e32 v243, v67
	v_mov_b32_e32 v67, v82
	v_add_f32_e32 v70, 1.0, v71
	v_rcp_f32_e32 v71, v70
	v_fma_f32 v70, -v243, v243, 1.0
	v_sqrt_f32_e32 v121, v70
	v_mul_f32_e32 v70, v82, v241
	v_pk_fma_f32 v[66:67], v[66:67], v[240:241], v[70:71] op_sel_hi:[1,1,0]
	v_mul_f32_e32 v144, v86, v243
	v_mul_f32_e32 v70, v71, v121
	v_mov_b32_e32 v71, v86
	v_pk_fma_f32 v[70:71], v[70:71], v[242:243], v[144:145] op_sel_hi:[1,1,0]
	v_mul_f32_e32 v75, v151, v91
	v_mul_f32_e32 v79, v153, v99
	v_mul_f32_e32 v65, v155, v81
	v_mul_f32_e32 v69, v147, v85
	v_mul_f32_e32 v67, v241, v83
	v_mul_f32_e32 v71, v243, v87
	v_fmamk_f32 v60, v60, 0xbfb8aa3b, v222
	v_exp_f32_e32 v60, v60
	v_fmamk_f32 v56, v56, 0xbfb8aa3b, v220
	v_exp_f32_e32 v56, v56
	v_fmamk_f32 v61, v61, 0xbfb8aa3b, v223
	v_add_f32_e32 v60, 1.0, v60
	v_rcp_f32_e32 v60, v60
	v_add_f32_e32 v56, 1.0, v56
	v_rcp_f32_e32 v56, v56
	v_exp_f32_e32 v121, v61
	v_mul_f32_e32 v60, v218, v60
	v_exp_f32_e32 v145, v60
	v_fmamk_f32 v57, v57, 0xbfb8aa3b, v221
	v_exp_f32_e32 v123, v57
	v_lshlrev_b32_e32 v146, 16, v141
	v_fma_f32 v60, -v145, v145, 1.0
	v_sqrt_f32_e32 v60, v60
	v_and_b32_e32 v148, 0xffff0000, v141
	v_lshlrev_b32_e32 v144, 16, v140
	v_mov_b32_e32 v61, v72
	v_mul_f32_e32 v60, v56, v60
	v_add_f32_e32 v56, 1.0, v121
	v_rcp_f32_e32 v121, v56
	v_mul_f32_e32 v56, v72, v145
	v_fmamk_f32 v58, v58, 0xbfb8aa3b, v214
	v_exp_f32_e32 v58, v58
	v_mul_f32_e32 v57, v219, v121
	v_exp_f32_e32 v141, v57
	v_pk_fma_f32 v[56:57], v[60:61], v[144:145], v[56:57] op_sel_hi:[1,1,0]
	v_and_b32_e32 v140, 0xffff0000, v140
	v_add_f32_e32 v57, 1.0, v123
	v_rcp_f32_e32 v60, v57
	v_fma_f32 v57, -v141, v141, 1.0
	v_sqrt_f32_e32 v61, v57
	v_fmamk_f32 v57, v62, 0xbfb8aa3b, v216
	v_exp_f32_e32 v62, v57
	v_add_f32_e32 v58, 1.0, v58
	v_mul_f32_e32 v60, v60, v61
	v_mov_b32_e32 v61, v76
	v_add_f32_e32 v62, 1.0, v62
	v_rcp_f32_e32 v121, v62
	v_mul_f32_e32 v62, v76, v141
	v_pk_fma_f32 v[60:61], v[60:61], v[140:141], v[62:63] op_sel_hi:[1,1,0]
	v_rcp_f32_e32 v58, v58
	v_mul_f32_e32 v121, v212, v121
	v_exp_f32_e32 v147, v121
	v_fmamk_f32 v52, v52, 0xbfb8aa3b, v210
	v_exp_f32_e32 v52, v52
	v_fmamk_f32 v59, v59, 0xbfb8aa3b, v215
	v_fma_f32 v61, -v147, v147, 1.0
	v_sqrt_f32_e32 v62, v61
	v_fmamk_f32 v61, v63, 0xbfb8aa3b, v217
	v_exp_f32_e32 v121, v61
	v_exp_f32_e32 v123, v59
	v_mul_f32_e32 v62, v58, v62
	v_add_f32_e32 v52, 1.0, v52
	v_add_f32_e32 v58, 1.0, v121
	v_rcp_f32_e32 v121, v58
	v_mov_b32_e32 v63, v74
	v_mul_f32_e32 v58, v74, v147
	v_fmamk_f32 v48, v48, 0xbfb8aa3b, v208
	v_mul_f32_e32 v59, v213, v121
	v_exp_f32_e32 v149, v59
	v_rcp_f32_e32 v121, v52
	v_pk_fma_f32 v[58:59], v[62:63], v[146:147], v[58:59] op_sel_hi:[1,1,0]
	v_exp_f32_e32 v48, v48
	v_add_f32_e32 v59, 1.0, v123
	v_rcp_f32_e32 v62, v59
	v_fma_f32 v59, -v149, v149, 1.0
	v_sqrt_f32_e32 v63, v59
	v_mul_f32_e32 v121, v206, v121
	v_exp_f32_e32 v151, v121
	v_mul_f32_e32 v52, v78, v149
	v_mul_f32_e32 v62, v62, v63
	v_mov_b32_e32 v63, v78
	v_pk_fma_f32 v[62:63], v[62:63], v[148:149], v[52:53] op_sel_hi:[1,1,0]
	v_add_f32_e32 v48, 1.0, v48
	v_fma_f32 v52, -v151, v151, 1.0
	v_fmamk_f32 v53, v53, 0xbfb8aa3b, v211
	v_rcp_f32_e32 v48, v48
	v_sqrt_f32_e32 v52, v52
	v_exp_f32_e32 v121, v53
	v_fmamk_f32 v49, v49, 0xbfb8aa3b, v209
	v_exp_f32_e32 v123, v49
	v_mul_f32_e32 v52, v48, v52
	v_add_f32_e32 v48, 1.0, v121
	v_rcp_f32_e32 v121, v48
	v_lshlrev_b32_e32 v152, 16, v143
	v_and_b32_e32 v154, 0xffff0000, v143
	v_lshlrev_b32_e32 v150, 16, v142
	v_mul_f32_e32 v49, v207, v121
	v_exp_f32_e32 v143, v49
	v_mov_b32_e32 v53, v64
	v_mul_f32_e32 v48, v64, v151
	v_pk_fma_f32 v[48:49], v[52:53], v[150:151], v[48:49] op_sel_hi:[1,1,0]
	v_fmamk_f32 v50, v50, 0xbfb8aa3b, v202
	v_add_f32_e32 v49, 1.0, v123
	v_rcp_f32_e32 v52, v49
	v_fma_f32 v49, -v143, v143, 1.0
	v_sqrt_f32_e32 v53, v49
	v_fmamk_f32 v49, v54, 0xbfb8aa3b, v204
	v_exp_f32_e32 v54, v49
	v_and_b32_e32 v142, 0xffff0000, v142
	v_mul_f32_e32 v52, v52, v53
	v_mov_b32_e32 v53, v68
	v_add_f32_e32 v54, 1.0, v54
	v_rcp_f32_e32 v54, v54
	v_exp_f32_e32 v121, v50
	v_mul_f32_e32 v50, v68, v143
	v_pk_fma_f32 v[52:53], v[52:53], v[142:143], v[50:51] op_sel_hi:[1,1,0]
	v_fmamk_f32 v51, v51, 0xbfb8aa3b, v203
	v_mul_f32_e32 v53, v200, v54
	v_exp_f32_e32 v153, v53
	v_fmamk_f32 v53, v55, 0xbfb8aa3b, v205
	v_exp_f32_e32 v54, v53
	v_add_f32_e32 v50, 1.0, v121
	v_fma_f32 v53, -v153, v153, 1.0
	v_rcp_f32_e32 v50, v50
	v_add_f32_e32 v54, 1.0, v54
	v_sqrt_f32_e32 v55, v53
	v_rcp_f32_e32 v54, v54
	v_mul_f32_e32 v57, v145, v73
	v_mul_f32_e32 v61, v141, v77
	v_mul_f32_e32 v50, v50, v55
	v_exp_f32_e32 v55, v51
	v_mul_f32_e32 v51, v201, v54
	v_exp_f32_e32 v155, v51
	v_mov_b32_e32 v51, v66
	v_add_f32_e32 v54, 1.0, v55
	v_rcp_f32_e32 v55, v54
	v_fma_f32 v54, -v155, v155, 1.0
	v_sqrt_f32_e32 v121, v54
	v_mul_f32_e32 v54, v66, v153
	v_pk_fma_f32 v[50:51], v[50:51], v[152:153], v[54:55] op_sel_hi:[1,1,0]
	v_mul_f32_e32 v140, v70, v155
	v_mul_f32_e32 v54, v55, v121
	v_mov_b32_e32 v55, v70
	v_pk_fma_f32 v[54:55], v[54:55], v[154:155], v[140:141] op_sel_hi:[1,1,0]
	v_mul_f32_e32 v59, v147, v75
	v_mul_f32_e32 v63, v149, v79
	v_mul_f32_e32 v49, v151, v65
	v_mul_f32_e32 v53, v143, v69
	v_mul_f32_e32 v51, v153, v67
	v_mul_f32_e32 v55, v155, v71
	v_fmamk_f32 v44, v44, 0xbfb8aa3b, v222
	v_exp_f32_e32 v44, v44
	v_fmamk_f32 v40, v40, 0xbfb8aa3b, v220
	v_exp_f32_e32 v40, v40
	v_fmamk_f32 v45, v45, 0xbfb8aa3b, v223
	v_add_f32_e32 v44, 1.0, v44
	v_rcp_f32_e32 v44, v44
	v_add_f32_e32 v40, 1.0, v40
	v_rcp_f32_e32 v40, v40
	v_exp_f32_e32 v121, v45
	v_mul_f32_e32 v44, v218, v44
	v_exp_f32_e32 v141, v44
	v_fmamk_f32 v41, v41, 0xbfb8aa3b, v221
	v_exp_f32_e32 v123, v41
	v_lshlrev_b32_e32 v142, 16, v133
	v_fma_f32 v44, -v141, v141, 1.0
	v_sqrt_f32_e32 v44, v44
	v_and_b32_e32 v144, 0xffff0000, v133
	v_lshlrev_b32_e32 v140, 16, v132
	v_mov_b32_e32 v45, v56
	v_mul_f32_e32 v44, v40, v44
	v_add_f32_e32 v40, 1.0, v121
	v_rcp_f32_e32 v121, v40
	v_mul_f32_e32 v40, v56, v141
	v_fmamk_f32 v42, v42, 0xbfb8aa3b, v214
	v_exp_f32_e32 v42, v42
	v_mul_f32_e32 v41, v219, v121
	v_exp_f32_e32 v133, v41
	v_pk_fma_f32 v[40:41], v[44:45], v[140:141], v[40:41] op_sel_hi:[1,1,0]
	v_and_b32_e32 v132, 0xffff0000, v132
	v_add_f32_e32 v41, 1.0, v123
	v_rcp_f32_e32 v44, v41
	v_fma_f32 v41, -v133, v133, 1.0
	v_sqrt_f32_e32 v45, v41
	v_fmamk_f32 v41, v46, 0xbfb8aa3b, v216
	v_exp_f32_e32 v46, v41
	v_add_f32_e32 v42, 1.0, v42
	v_mul_f32_e32 v44, v44, v45
	v_mov_b32_e32 v45, v60
	v_add_f32_e32 v46, 1.0, v46
	v_rcp_f32_e32 v121, v46
	v_mul_f32_e32 v46, v60, v133
	v_pk_fma_f32 v[44:45], v[44:45], v[132:133], v[46:47] op_sel_hi:[1,1,0]
	v_rcp_f32_e32 v42, v42
	v_mul_f32_e32 v121, v212, v121
	v_exp_f32_e32 v143, v121
	v_fmamk_f32 v36, v36, 0xbfb8aa3b, v210
	v_exp_f32_e32 v36, v36
	v_fmamk_f32 v43, v43, 0xbfb8aa3b, v215
	v_fma_f32 v45, -v143, v143, 1.0
	v_sqrt_f32_e32 v46, v45
	v_fmamk_f32 v45, v47, 0xbfb8aa3b, v217
	v_exp_f32_e32 v121, v45
	v_exp_f32_e32 v123, v43
	v_mul_f32_e32 v46, v42, v46
	v_add_f32_e32 v36, 1.0, v36
	v_add_f32_e32 v42, 1.0, v121
	v_rcp_f32_e32 v121, v42
	v_mov_b32_e32 v47, v58
	v_mul_f32_e32 v42, v58, v143
	v_fmamk_f32 v32, v32, 0xbfb8aa3b, v208
	v_mul_f32_e32 v43, v213, v121
	v_exp_f32_e32 v145, v43
	v_rcp_f32_e32 v121, v36
	v_pk_fma_f32 v[42:43], v[46:47], v[142:143], v[42:43] op_sel_hi:[1,1,0]
	v_exp_f32_e32 v32, v32
	v_add_f32_e32 v43, 1.0, v123
	v_rcp_f32_e32 v46, v43
	v_fma_f32 v43, -v145, v145, 1.0
	v_sqrt_f32_e32 v47, v43
	v_mul_f32_e32 v121, v206, v121
	v_exp_f32_e32 v147, v121
	v_mul_f32_e32 v36, v62, v145
	v_mul_f32_e32 v46, v46, v47
	v_mov_b32_e32 v47, v62
	v_pk_fma_f32 v[46:47], v[46:47], v[144:145], v[36:37] op_sel_hi:[1,1,0]
	v_add_f32_e32 v32, 1.0, v32
	v_fma_f32 v36, -v147, v147, 1.0
	v_fmamk_f32 v37, v37, 0xbfb8aa3b, v211
	v_rcp_f32_e32 v32, v32
	v_sqrt_f32_e32 v36, v36
	v_exp_f32_e32 v121, v37
	v_fmamk_f32 v33, v33, 0xbfb8aa3b, v209
	v_exp_f32_e32 v123, v33
	v_mul_f32_e32 v36, v32, v36
	v_add_f32_e32 v32, 1.0, v121
	v_rcp_f32_e32 v121, v32
	v_lshlrev_b32_e32 v148, 16, v135
	v_and_b32_e32 v150, 0xffff0000, v135
	v_lshlrev_b32_e32 v146, 16, v134
	v_mul_f32_e32 v33, v207, v121
	v_exp_f32_e32 v135, v33
	v_mov_b32_e32 v37, v48
	v_mul_f32_e32 v32, v48, v147
	v_pk_fma_f32 v[32:33], v[36:37], v[146:147], v[32:33] op_sel_hi:[1,1,0]
	v_fmamk_f32 v34, v34, 0xbfb8aa3b, v202
	v_add_f32_e32 v33, 1.0, v123
	v_rcp_f32_e32 v36, v33
	v_fma_f32 v33, -v135, v135, 1.0
	v_sqrt_f32_e32 v37, v33
	v_fmamk_f32 v33, v38, 0xbfb8aa3b, v204
	v_exp_f32_e32 v38, v33
	v_and_b32_e32 v134, 0xffff0000, v134
	v_mul_f32_e32 v36, v36, v37
	v_mov_b32_e32 v37, v52
	v_add_f32_e32 v38, 1.0, v38
	v_rcp_f32_e32 v38, v38
	v_exp_f32_e32 v121, v34
	v_mul_f32_e32 v34, v52, v135
	v_pk_fma_f32 v[36:37], v[36:37], v[134:135], v[34:35] op_sel_hi:[1,1,0]
	v_fmamk_f32 v35, v35, 0xbfb8aa3b, v203
	v_mul_f32_e32 v37, v200, v38
	v_exp_f32_e32 v149, v37
	v_fmamk_f32 v37, v39, 0xbfb8aa3b, v205
	v_exp_f32_e32 v38, v37
	v_add_f32_e32 v34, 1.0, v121
	v_fma_f32 v37, -v149, v149, 1.0
	v_rcp_f32_e32 v34, v34
	v_add_f32_e32 v38, 1.0, v38
	v_sqrt_f32_e32 v39, v37
	v_rcp_f32_e32 v38, v38
	v_mul_f32_e32 v41, v141, v57
	v_mul_f32_e32 v45, v133, v61
	v_mul_f32_e32 v34, v34, v39
	v_exp_f32_e32 v39, v35
	v_mul_f32_e32 v35, v201, v38
	v_exp_f32_e32 v151, v35
	v_mov_b32_e32 v35, v50
	v_add_f32_e32 v38, 1.0, v39
	v_rcp_f32_e32 v39, v38
	v_fma_f32 v38, -v151, v151, 1.0
	v_sqrt_f32_e32 v121, v38
	v_mul_f32_e32 v38, v50, v149
	v_pk_fma_f32 v[34:35], v[34:35], v[148:149], v[38:39] op_sel_hi:[1,1,0]
	v_mul_f32_e32 v132, v54, v151
	v_mul_f32_e32 v38, v39, v121
	v_mov_b32_e32 v39, v54
	v_pk_fma_f32 v[38:39], v[38:39], v[150:151], v[132:133] op_sel_hi:[1,1,0]
	v_mul_f32_e32 v43, v143, v59
	v_mul_f32_e32 v47, v145, v63
	v_mul_f32_e32 v33, v147, v49
	v_mul_f32_e32 v37, v135, v53
	v_mul_f32_e32 v35, v149, v51
	v_mul_f32_e32 v39, v151, v55
	v_fmamk_f32 v28, v28, 0xbfb8aa3b, v222
	v_lshlrev_b32_e32 v132, 16, v112
	v_and_b32_e32 v134, 0xffff0000, v112
	v_exp_f32_e32 v112, v28
	v_fmamk_f32 v29, v29, 0xbfb8aa3b, v223
	v_exp_f32_e32 v29, v29
	v_fmamk_f32 v24, v24, 0xbfb8aa3b, v220
	v_add_f32_e32 v112, 1.0, v112
	v_rcp_f32_e32 v112, v112
	v_add_f32_e32 v29, 1.0, v29
	v_rcp_f32_e32 v29, v29
	v_lshlrev_b32_e32 v28, 16, v113
	v_and_b32_e32 v140, 0xffff0000, v113
	v_exp_f32_e32 v113, v24
	v_mul_f32_e32 v24, v218, v112
	v_exp_f32_e32 v133, v24
	v_fmamk_f32 v25, v25, 0xbfb8aa3b, v221
	v_mul_f32_e32 v29, v219, v29
	v_exp_f32_e32 v25, v25
	v_exp_f32_e32 v135, v29
	v_add_f32_e32 v112, 1.0, v113
	v_fma_f32 v113, -v133, v133, 1.0
	v_rcp_f32_e32 v112, v112
	v_sqrt_f32_e32 v113, v113
	v_add_f32_e32 v25, 1.0, v25
	v_fma_f32 v29, -v135, v135, 1.0
	v_fmamk_f32 v30, v30, 0xbfb8aa3b, v216
	v_rcp_f32_e32 v25, v25
	v_sqrt_f32_e32 v29, v29
	v_exp_f32_e32 v30, v30
	v_lshlrev_b32_e32 v142, 16, v114
	v_and_b32_e32 v144, 0xffff0000, v114
	v_mul_f32_e32 v112, v112, v113
	v_mov_b32_e32 v113, v40
	v_mul_f32_e32 v114, v40, v133
	v_pk_fma_f32 v[112:113], v[112:113], v[132:133], v[114:115] op_sel_hi:[1,1,0]
	v_mul_f32_e32 v114, v25, v29
	v_add_f32_e32 v25, 1.0, v30
	v_rcp_f32_e32 v25, v25
	v_fmamk_f32 v26, v26, 0xbfb8aa3b, v214
	v_exp_f32_e32 v26, v26
	v_lshlrev_b32_e32 v24, 16, v115
	v_mul_f32_e32 v25, v212, v25
	v_exp_f32_e32 v29, v25
	v_and_b32_e32 v148, 0xffff0000, v115
	v_mov_b32_e32 v115, v44
	v_mul_f32_e32 v30, v44, v135
	v_pk_fma_f32 v[114:115], v[114:115], v[134:135], v[30:31] op_sel_hi:[1,1,0]
	v_add_f32_e32 v25, 1.0, v26
	v_fma_f32 v26, -v29, v29, 1.0
	v_fmamk_f32 v30, v31, 0xbfb8aa3b, v217
	v_rcp_f32_e32 v25, v25
	v_sqrt_f32_e32 v26, v26
	v_exp_f32_e32 v121, v30
	v_fmamk_f32 v27, v27, 0xbfb8aa3b, v215
	v_exp_f32_e32 v27, v27
	v_mul_f32_e32 v30, v25, v26
	v_add_f32_e32 v25, 1.0, v121
	v_rcp_f32_e32 v25, v25
	v_mov_b32_e32 v31, v42
	v_mul_f32_e32 v26, v42, v29
	v_fmamk_f32 v20, v20, 0xbfb8aa3b, v210
	v_mul_f32_e32 v25, v213, v25
	v_exp_f32_e32 v141, v25
	v_mul_f32_e32 v113, v133, v41
	v_pk_fma_f32 v[132:133], v[30:31], v[28:29], v[26:27] op_sel_hi:[1,1,0]
	v_add_f32_e32 v25, 1.0, v27
	v_fma_f32 v26, -v141, v141, 1.0
	v_exp_f32_e32 v20, v20
	v_rcp_f32_e32 v25, v25
	v_sqrt_f32_e32 v26, v26
	v_fmamk_f32 v16, v16, 0xbfb8aa3b, v208
	v_add_f32_e32 v20, 1.0, v20
	v_exp_f32_e32 v16, v16
	v_mul_f32_e32 v26, v25, v26
	v_rcp_f32_e32 v25, v20
	v_mov_b32_e32 v27, v46
	v_mul_f32_e32 v20, v46, v141
	v_mul_f32_e32 v115, v135, v45
	v_mul_f32_e32 v25, v206, v25
	v_exp_f32_e32 v143, v25
	v_pk_fma_f32 v[134:135], v[26:27], v[140:141], v[20:21] op_sel_hi:[1,1,0]
	v_add_f32_e32 v16, 1.0, v16
	v_fmamk_f32 v21, v21, 0xbfb8aa3b, v211
	v_fma_f32 v20, -v143, v143, 1.0
	v_rcp_f32_e32 v16, v16
	v_sqrt_f32_e32 v20, v20
	v_exp_f32_e32 v25, v21
	v_fmamk_f32 v17, v17, 0xbfb8aa3b, v209
	v_exp_f32_e32 v17, v17
	v_mul_f32_e32 v20, v16, v20
	v_add_f32_e32 v16, 1.0, v25
	v_rcp_f32_e32 v25, v16
	v_mov_b32_e32 v21, v32
	v_mul_f32_e32 v16, v32, v143
	v_mul_f32_e32 v123, v141, v47
	v_mul_f32_e32 v25, v207, v25
	v_exp_f32_e32 v145, v25
	v_pk_fma_f32 v[140:141], v[20:21], v[142:143], v[16:17] op_sel_hi:[1,1,0]
	v_fmamk_f32 v20, v22, 0xbfb8aa3b, v204
	v_exp_f32_e32 v20, v20
	v_add_f32_e32 v16, 1.0, v17
	v_fma_f32 v17, -v145, v145, 1.0
	v_rcp_f32_e32 v16, v16
	v_sqrt_f32_e32 v17, v17
	v_add_f32_e32 v20, 1.0, v20
	v_rcp_f32_e32 v20, v20
	v_fmamk_f32 v18, v18, 0xbfb8aa3b, v202
	v_mul_f32_e32 v16, v16, v17
	v_mov_b32_e32 v17, v36
	v_exp_f32_e32 v21, v18
	v_mul_f32_e32 v18, v36, v145
	v_mul_f32_e32 v125, v143, v33
	v_pk_fma_f32 v[142:143], v[16:17], v[144:145], v[18:19] op_sel_hi:[1,1,0]
	v_mul_f32_e32 v17, v200, v20
	v_exp_f32_e32 v25, v17
	v_fmamk_f32 v17, v23, 0xbfb8aa3b, v205
	v_exp_f32_e32 v17, v17
	v_add_f32_e32 v16, 1.0, v21
	v_fma_f32 v18, -v25, v25, 1.0
	v_rcp_f32_e32 v16, v16
	v_sqrt_f32_e32 v18, v18
	v_add_f32_e32 v17, 1.0, v17
	v_rcp_f32_e32 v17, v17
	v_mul_f32_e32 v127, v145, v37
	v_mul_f32_e32 v16, v16, v18
	v_fmamk_f32 v18, v19, 0xbfb8aa3b, v203
	v_exp_f32_e32 v18, v18
	v_mul_f32_e32 v17, v201, v17
	v_exp_f32_e32 v149, v17
	v_mov_b32_e32 v17, v34
	v_add_f32_e32 v18, 1.0, v18
	v_rcp_f32_e32 v19, v18
	v_fma_f32 v18, -v149, v149, 1.0
	v_sqrt_f32_e32 v20, v18
	v_mul_f32_e32 v18, v34, v25
	v_pk_fma_f32 v[144:145], v[16:17], v[24:25], v[18:19] op_sel_hi:[1,1,0]
	v_mov_b32_e32 v17, v38
	v_mul_f32_e32 v16, v19, v20
	v_mul_f32_e32 v18, v38, v149
	v_mul_f32_e32 v121, v29, v43
	v_mul_f32_e32 v129, v25, v35
	v_pk_fma_f32 v[146:147], v[16:17], v[148:149], v[18:19] op_sel_hi:[1,1,0]
	v_mul_f32_e32 v131, v149, v39
	v_fmamk_f32 v12, v12, 0xbfb8aa3b, v222
	v_exp_f32_e32 v17, v12
	v_fmamk_f32 v8, v8, 0xbfb8aa3b, v220
	v_fmac_f32_e32 v223, 0xbfb8aa3b, v13
	v_exp_f32_e32 v19, v8
	v_add_f32_e32 v17, 1.0, v17
	v_rcp_f32_e32 v17, v17
	v_exp_f32_e32 v13, v223
	v_add_f32_e32 v19, 1.0, v19
	v_rcp_f32_e32 v19, v19
	v_mul_f32_e32 v8, v218, v17
	v_exp_f32_e32 v17, v8
	v_add_f32_e32 v13, 1.0, v13
	v_rcp_f32_e32 v13, v13
	v_fmac_f32_e32 v221, 0xbfb8aa3b, v9
	v_fma_f32 v21, -v17, v17, 1.0
	v_sqrt_f32_e32 v21, v21
	v_mul_f32_e32 v13, v219, v13
	v_exp_f32_e32 v9, v221
	v_fmamk_f32 v14, v14, 0xbfb8aa3b, v216
	v_mul_f32_e32 v28, v19, v21
	v_exp_f32_e32 v19, v13
	v_add_f32_e32 v9, 1.0, v9
	v_rcp_f32_e32 v9, v9
	v_exp_f32_e32 v14, v14
	v_fma_f32 v13, -v19, v19, 1.0
	v_sqrt_f32_e32 v13, v13
	v_lshlrev_b32_e32 v16, 16, v92
	v_mov_b32_e32 v29, v112
	v_pk_mul_f32 v[28:29], v[28:29], v[16:17]
	v_mul_f32_e32 v16, v9, v13
	v_add_f32_e32 v9, 1.0, v14
	v_rcp_f32_e32 v9, v9
	v_fmamk_f32 v10, v10, 0xbfb8aa3b, v214
	v_exp_f32_e32 v10, v10
	v_and_b32_e32 v18, 0xffff0000, v92
	v_mul_f32_e32 v9, v212, v9
	v_exp_f32_e32 v13, v9
	v_mul_f32_e32 v135, v17, v113
	v_mov_b32_e32 v17, v114
	v_pk_mul_f32 v[16:17], v[16:17], v[18:19]
	v_add_f32_e32 v9, 1.0, v10
	v_fma_f32 v10, -v13, v13, 1.0
	v_fmac_f32_e32 v217, 0xbfb8aa3b, v15
	v_add_f32_e32 v137, v16, v17
	v_rcp_f32_e32 v9, v9
	v_sqrt_f32_e32 v10, v10
	v_exp_f32_e32 v16, v217
	v_fmamk_f32 v4, v4, 0xbfb8aa3b, v210
	v_exp_f32_e32 v4, v4
	v_mul_f32_e32 v14, v9, v10
	v_add_f32_e32 v9, 1.0, v16
	v_rcp_f32_e32 v9, v9
	v_add_f32_e32 v4, 1.0, v4
	v_fmac_f32_e32 v215, 0xbfb8aa3b, v11
	v_rcp_f32_e32 v4, v4
	v_mul_f32_e32 v9, v213, v9
	v_exp_f32_e32 v10, v215
	v_exp_f32_e32 v21, v9
	v_fmamk_f32 v0, v0, 0xbfb8aa3b, v208
	v_mul_f32_e32 v4, v206, v4
	v_add_f32_e32 v9, 1.0, v10
	v_fma_f32 v10, -v21, v21, 1.0
	v_exp_f32_e32 v0, v0
	v_exp_f32_e32 v23, v4
	v_rcp_f32_e32 v9, v9
	v_sqrt_f32_e32 v10, v10
	v_add_f32_e32 v0, 1.0, v0
	v_fma_f32 v4, -v23, v23, 1.0
	v_fmac_f32_e32 v211, 0xbfb8aa3b, v5
	v_mul_f32_e32 v10, v9, v10
	v_rcp_f32_e32 v0, v0
	v_sqrt_f32_e32 v4, v4
	v_exp_f32_e32 v9, v211
	v_lshlrev_b32_e32 v22, 16, v94
	v_mov_b32_e32 v5, v140
	v_mul_f32_e32 v4, v0, v4
	v_add_f32_e32 v0, 1.0, v9
	v_rcp_f32_e32 v0, v0
	v_fmac_f32_e32 v209, 0xbfb8aa3b, v1
	v_pk_mul_f32 v[4:5], v[4:5], v[22:23]
	v_exp_f32_e32 v1, v209
	v_mul_f32_e32 v0, v207, v0
	v_exp_f32_e32 v25, v0
	v_add_f32_e32 v147, v4, v5
	v_fmamk_f32 v4, v6, 0xbfb8aa3b, v204
	v_exp_f32_e32 v4, v4
	v_add_f32_e32 v0, 1.0, v1
	v_fma_f32 v1, -v25, v25, 1.0
	v_rcp_f32_e32 v0, v0
	v_sqrt_f32_e32 v1, v1
	v_add_f32_e32 v4, 1.0, v4
	v_rcp_f32_e32 v4, v4
	v_and_b32_e32 v24, 0xffff0000, v94
	v_mul_f32_e32 v0, v0, v1
	v_mov_b32_e32 v1, v142
	v_pk_mul_f32 v[0:1], v[0:1], v[24:25]
	v_fmac_f32_e32 v205, 0xbfb8aa3b, v7
	v_add_f32_e32 v187, v0, v1
	v_mul_f32_e32 v1, v200, v4
	v_fmamk_f32 v2, v2, 0xbfb8aa3b, v202
	v_exp_f32_e32 v9, v1
	v_exp_f32_e32 v1, v205
	v_exp_f32_e32 v2, v2
	v_fmac_f32_e32 v203, 0xbfb8aa3b, v3
	v_lshlrev_b32_e32 v8, 16, v95
	v_add_f32_e32 v1, 1.0, v1
	v_add_f32_e32 v0, 1.0, v2
	v_fma_f32 v2, -v9, v9, 1.0
	v_rcp_f32_e32 v1, v1
	v_rcp_f32_e32 v0, v0
	v_sqrt_f32_e32 v2, v2
	v_lshlrev_b32_e32 v12, 16, v93
	v_mul_f32_e32 v1, v201, v1
	v_exp_f32_e32 v27, v1
	v_mul_f32_e32 v0, v0, v2
	v_exp_f32_e32 v2, v203
	v_mov_b32_e32 v1, v144
	v_fma_f32 v3, -v27, v27, 1.0
	v_sqrt_f32_e32 v3, v3
	v_add_f32_e32 v2, 1.0, v2
	v_rcp_f32_e32 v2, v2
	v_pk_mul_f32 v[0:1], v[0:1], v[8:9]
	v_and_b32_e32 v20, 0xffff0000, v93
	v_and_b32_e32 v26, 0xffff0000, v95
	v_mov_b32_e32 v15, v132
	v_mov_b32_e32 v11, v134
	v_add_f32_e32 v193, v0, v1
	v_mul_f32_e32 v0, v2, v3
	v_mov_b32_e32 v1, v146
	v_pk_mul_f32 v[14:15], v[14:15], v[12:13]
	v_pk_mul_f32 v[10:11], v[10:11], v[20:21]
	v_pk_mul_f32 v[0:1], v[0:1], v[26:27]
	v_add_f32_e32 v133, v28, v29
	v_mul_f32_e32 v141, v19, v115
	v_add_f32_e32 v139, v14, v15
	v_mul_f32_e32 v143, v13, v121
	v_add_f32_e32 v145, v10, v11
	v_mul_f32_e32 v185, v21, v123
	v_mul_f32_e32 v189, v23, v125
	v_mul_f32_e32 v191, v25, v127
	v_mul_f32_e32 v197, v9, v129
	v_add_f32_e32 v195, v0, v1
	v_mul_f32_e32 v199, v27, v131
	v_mov_b32_e32 v0, v135
	v_mov_b32_e32 v17, v133
	v_mov_b32_e32 v2, v141
	v_mov_b32_e32 v19, v137
	v_mov_b32_e32 v4, v143
	v_mov_b32_e32 v21, v139
	v_mov_b32_e32 v6, v185
	v_mov_b32_e32 v23, v145
	v_mov_b32_e32 v8, v189
	v_mov_b32_e32 v25, v147
	v_mov_b32_e32 v10, v191
	v_mov_b32_e32 v27, v187
	v_mov_b32_e32 v12, v197
	v_mov_b32_e32 v31, v193
	v_mov_b32_e32 v14, v199
	v_mov_b32_e32 v205, v195
	v_fmac_f32_dpp v17, v17, v0 row_shr:1 row_mask:0xf bank_mask:0xf
	v_fmac_f32_dpp v19, v19, v2 row_shr:1 row_mask:0xf bank_mask:0xf
	v_fmac_f32_dpp v21, v21, v4 row_shr:1 row_mask:0xf bank_mask:0xf
	v_fmac_f32_dpp v23, v23, v6 row_shr:1 row_mask:0xf bank_mask:0xf
	v_fmac_f32_dpp v25, v25, v8 row_shr:1 row_mask:0xf bank_mask:0xf
	v_fmac_f32_dpp v27, v27, v10 row_shr:1 row_mask:0xf bank_mask:0xf
	v_fmac_f32_dpp v31, v31, v12 row_shr:1 row_mask:0xf bank_mask:0xf
	v_fmac_f32_dpp v205, v205, v14 row_shr:1 row_mask:0xf bank_mask:0xf
	v_mul_f32_dpp v0, v0, v0 row_shr:1 row_mask:0xf bank_mask:0xf
	v_mul_f32_dpp v2, v2, v2 row_shr:1 row_mask:0xf bank_mask:0xf
	v_mul_f32_dpp v4, v4, v4 row_shr:1 row_mask:0xf bank_mask:0xf
	v_mul_f32_dpp v6, v6, v6 row_shr:1 row_mask:0xf bank_mask:0xf
	v_mul_f32_dpp v8, v8, v8 row_shr:1 row_mask:0xf bank_mask:0xf
	v_mul_f32_dpp v10, v10, v10 row_shr:1 row_mask:0xf bank_mask:0xf
	v_mul_f32_dpp v12, v12, v12 row_shr:1 row_mask:0xf bank_mask:0xf
	v_mul_f32_dpp v14, v14, v14 row_shr:1 row_mask:0xf bank_mask:0xf
	v_fmac_f32_dpp v17, v17, v0 row_shr:2 row_mask:0xf bank_mask:0xf
	v_fmac_f32_dpp v19, v19, v2 row_shr:2 row_mask:0xf bank_mask:0xf
	v_fmac_f32_dpp v21, v21, v4 row_shr:2 row_mask:0xf bank_mask:0xf
	v_fmac_f32_dpp v23, v23, v6 row_shr:2 row_mask:0xf bank_mask:0xf
	v_fmac_f32_dpp v25, v25, v8 row_shr:2 row_mask:0xf bank_mask:0xf
	v_fmac_f32_dpp v27, v27, v10 row_shr:2 row_mask:0xf bank_mask:0xf
	v_fmac_f32_dpp v31, v31, v12 row_shr:2 row_mask:0xf bank_mask:0xf
	v_fmac_f32_dpp v205, v205, v14 row_shr:2 row_mask:0xf bank_mask:0xf
	v_mul_f32_dpp v0, v0, v0 row_shr:2 row_mask:0xf bank_mask:0xf
	v_mul_f32_dpp v2, v2, v2 row_shr:2 row_mask:0xf bank_mask:0xf
	v_mul_f32_dpp v4, v4, v4 row_shr:2 row_mask:0xf bank_mask:0xf
	v_mul_f32_dpp v6, v6, v6 row_shr:2 row_mask:0xf bank_mask:0xf
	v_mul_f32_dpp v8, v8, v8 row_shr:2 row_mask:0xf bank_mask:0xf
	v_mul_f32_dpp v10, v10, v10 row_shr:2 row_mask:0xf bank_mask:0xf
	v_mul_f32_dpp v12, v12, v12 row_shr:2 row_mask:0xf bank_mask:0xf
	v_mul_f32_dpp v14, v14, v14 row_shr:2 row_mask:0xf bank_mask:0xf
	v_fmac_f32_dpp v17, v17, v0 row_shr:4 row_mask:0xf bank_mask:0xf
	v_fmac_f32_dpp v19, v19, v2 row_shr:4 row_mask:0xf bank_mask:0xf
	v_fmac_f32_dpp v21, v21, v4 row_shr:4 row_mask:0xf bank_mask:0xf
	v_fmac_f32_dpp v23, v23, v6 row_shr:4 row_mask:0xf bank_mask:0xf
	v_fmac_f32_dpp v25, v25, v8 row_shr:4 row_mask:0xf bank_mask:0xf
	v_fmac_f32_dpp v27, v27, v10 row_shr:4 row_mask:0xf bank_mask:0xf
	v_fmac_f32_dpp v31, v31, v12 row_shr:4 row_mask:0xf bank_mask:0xf
	v_fmac_f32_dpp v205, v205, v14 row_shr:4 row_mask:0xf bank_mask:0xf
	v_mul_f32_dpp v0, v0, v0 row_shr:4 row_mask:0xf bank_mask:0xf
	v_mul_f32_dpp v2, v2, v2 row_shr:4 row_mask:0xf bank_mask:0xf
	v_mul_f32_dpp v4, v4, v4 row_shr:4 row_mask:0xf bank_mask:0xf
	v_mul_f32_dpp v6, v6, v6 row_shr:4 row_mask:0xf bank_mask:0xf
	v_mul_f32_dpp v8, v8, v8 row_shr:4 row_mask:0xf bank_mask:0xf
	v_mul_f32_dpp v10, v10, v10 row_shr:4 row_mask:0xf bank_mask:0xf
	v_mul_f32_dpp v12, v12, v12 row_shr:4 row_mask:0xf bank_mask:0xf
	v_mul_f32_dpp v14, v14, v14 row_shr:4 row_mask:0xf bank_mask:0xf
	v_mul_f32_dpp v1, v17, v0 row_shr:8 row_mask:0xf bank_mask:0xf bound_ctrl:1
	v_mul_f32_dpp v3, v19, v2 row_shr:8 row_mask:0xf bank_mask:0xf bound_ctrl:1
	v_mul_f32_dpp v5, v21, v4 row_shr:8 row_mask:0xf bank_mask:0xf bound_ctrl:1
	v_mul_f32_dpp v7, v23, v6 row_shr:8 row_mask:0xf bank_mask:0xf bound_ctrl:1
	v_mul_f32_dpp v9, v25, v8 row_shr:8 row_mask:0xf bank_mask:0xf bound_ctrl:1
	v_mul_f32_dpp v11, v27, v10 row_shr:8 row_mask:0xf bank_mask:0xf bound_ctrl:1
	v_mul_f32_dpp v13, v31, v12 row_shr:8 row_mask:0xf bank_mask:0xf bound_ctrl:1
	v_mul_f32_dpp v15, v205, v14 row_shr:8 row_mask:0xf bank_mask:0xf bound_ctrl:1
	v_mul_f32_dpp v0, v0, v0 row_shr:8 row_mask:0xf bank_mask:0xf
	v_mul_f32_dpp v2, v2, v2 row_shr:8 row_mask:0xf bank_mask:0xf
	v_mul_f32_dpp v4, v4, v4 row_shr:8 row_mask:0xf bank_mask:0xf
	v_mul_f32_dpp v6, v6, v6 row_shr:8 row_mask:0xf bank_mask:0xf
	v_mul_f32_dpp v8, v8, v8 row_shr:8 row_mask:0xf bank_mask:0xf
	v_mul_f32_dpp v10, v10, v10 row_shr:8 row_mask:0xf bank_mask:0xf
	v_mul_f32_dpp v12, v12, v12 row_shr:8 row_mask:0xf bank_mask:0xf
	v_mul_f32_dpp v14, v14, v14 row_shr:8 row_mask:0xf bank_mask:0xf
	v_add_f32_e32 v17, v1, v17
	v_add_f32_e32 v19, v3, v19
	v_add_f32_e32 v21, v5, v21
	v_add_f32_e32 v23, v7, v23
	v_add_f32_e32 v25, v9, v25
	v_add_f32_e32 v27, v11, v27
	v_add_f32_e32 v31, v13, v31
	v_add_f32_e32 v205, v15, v205
	v_mov_b32_e32 v93, 1.0
	v_mov_b32_e32 v95, 1.0
	v_mov_b32_e32 v149, 1.0
	v_mov_b32_e32 v151, 1.0
	v_mov_b32_e32 v153, 1.0
	v_mov_b32_e32 v155, 1.0
	v_mov_b32_e32 v201, 1.0
	v_mov_b32_e32 v203, 1.0
	v_lshlrev_b32_e32 v1, 6, v237
	v_cmp_eq_u32_e64 s[8:9], 15, v239
	v_mov_b32_dpp v93, v0 row_shr:1 row_mask:0xf bank_mask:0xf
	v_mov_b32_dpp v92, v17 row_shr:1 row_mask:0xf bank_mask:0xf bound_ctrl:1
	v_mov_b32_dpp v95, v2 row_shr:1 row_mask:0xf bank_mask:0xf
	v_mov_b32_dpp v94, v19 row_shr:1 row_mask:0xf bank_mask:0xf bound_ctrl:1
	v_mov_b32_dpp v149, v4 row_shr:1 row_mask:0xf bank_mask:0xf
	v_mov_b32_dpp v148, v21 row_shr:1 row_mask:0xf bank_mask:0xf bound_ctrl:1
	v_mov_b32_dpp v151, v6 row_shr:1 row_mask:0xf bank_mask:0xf
	v_mov_b32_dpp v150, v23 row_shr:1 row_mask:0xf bank_mask:0xf bound_ctrl:1
	v_mov_b32_dpp v153, v8 row_shr:1 row_mask:0xf bank_mask:0xf
	v_mov_b32_dpp v152, v25 row_shr:1 row_mask:0xf bank_mask:0xf bound_ctrl:1
	v_mov_b32_dpp v155, v10 row_shr:1 row_mask:0xf bank_mask:0xf
	v_mov_b32_dpp v154, v27 row_shr:1 row_mask:0xf bank_mask:0xf bound_ctrl:1
	v_mov_b32_dpp v201, v12 row_shr:1 row_mask:0xf bank_mask:0xf
	v_mov_b32_dpp v200, v31 row_shr:1 row_mask:0xf bank_mask:0xf bound_ctrl:1
	v_mov_b32_dpp v203, v14 row_shr:1 row_mask:0xf bank_mask:0xf
	v_mov_b32_dpp v202, v205 row_shr:1 row_mask:0xf bank_mask:0xf bound_ctrl:1
	s_and_b64 s[20:21], s[46:47], s[8:9]
	v_add_u32_e32 v171, s17, v1
	s_and_saveexec_b64 s[6:7], s[20:21]
	s_cbranch_execz .LBB0_466
	v_mov_b32_e32 v1, v17
	v_mov_b32_e32 v3, v19
	v_mov_b32_e32 v5, v21
	v_mov_b32_e32 v7, v23
	v_mov_b32_e32 v9, v25
	v_mov_b32_e32 v11, v27
	v_mov_b32_e32 v13, v31
	v_mov_b32_e32 v15, v205
	ds_write_b128 v171, v[0:3]
	ds_write_b128 v171, v[4:7] offset:16
	ds_write_b128 v171, v[8:11] offset:32
	ds_write_b128 v171, v[12:15] offset:48
